# residual epilogue: straight-line pipelined paths also for the f32-input form (layer-0 first down phase) and the final f32-output form
# baseline (speedup 1.0000x reference)
.LBB0_350:
	v_readlane_b32 s64, v254, 33
	v_readlane_b32 s65, v254, 34
	v_readlane_b32 s66, v254, 36
	v_readlane_b32 s67, v254, 37
	s_and_b64 vcc, exec, s[64:65]
	s_cbranch_vccz .Lepr_fromin
	s_and_b64 vcc, exec, s[66:67]
	s_cbranch_vccz .Lepr_last
	s_load_dwordx4 s[64:67], s[0:1], 0xb8
	s_lshl_b32 s17, s34, 8
	s_mov_b64 s[52:53], 0x8000
	s_mov_b64 s[14:15], 0x28000
	v_add_u32_e32 v134, s17, v241
	v_ashrrev_i32_e32 v135, 31, v134
	v_lshlrev_b64 v[134:135], 11, v[134:135]
	v_lshl_add_u64 v[134:135], v[220:221], 1, v[134:135]
	s_waitcnt lgkmcnt(0)
	s_add_u32 s54, s66, 0xe800000
	s_addc_u32 s55, s67, 0
	v_lshl_add_u64 v[220:221], v[134:135], 0, s[54:55]
	v_mov_b32_e32 v216, v220
	v_mov_b32_e32 v217, v221
	s_add_u32 s54, s66, 0x6000000
	s_addc_u32 s55, s67, 0
	v_lshl_add_u64 v[218:219], v[134:135], 0, s[54:55]
	global_load_dwordx4 v[154:157], v[220:221], off
	global_load_dwordx4 v[158:161], v[220:221], off offset:256
	v_lshl_add_u64 v[220:221], v[220:221], 0, s[52:53]
	global_load_dwordx4 v[162:165], v[220:221], off
	global_load_dwordx4 v[166:169], v[220:221], off offset:256
	v_lshl_add_u64 v[220:221], v[220:221], 0, s[52:53]
	global_load_dwordx4 v[170:173], v[220:221], off
	global_load_dwordx4 v[174:177], v[220:221], off offset:256
	v_lshl_add_u64 v[220:221], v[220:221], 0, s[52:53]
	global_load_dwordx4 v[130:133], v[220:221], off
	global_load_dwordx4 v[134:137], v[220:221], off offset:256
	v_lshl_add_u64 v[220:221], v[220:221], 0, s[14:15]
	v_pk_mul_f32 v[146:147], v[146:147], v[192:193]
	v_pk_mul_f32 v[148:149], v[148:149], v[192:193]
	v_pk_mul_f32 v[150:151], v[150:151], v[192:193]
	v_pk_mul_f32 v[152:153], v[152:153], v[192:193]
	v_pk_mul_f32 v[138:139], v[138:139], v[192:193]
	v_pk_mul_f32 v[140:141], v[140:141], v[192:193]
	v_pk_mul_f32 v[142:143], v[142:143], v[192:193]
	v_pk_mul_f32 v[144:145], v[144:145], v[192:193]
	s_waitcnt vmcnt(7)
	v_lshlrev_b32_e32 v222, 16, v154
	v_and_b32_e32 v223, 0xffff0000, v154
	v_lshlrev_b32_e32 v224, 16, v156
	v_and_b32_e32 v225, 0xffff0000, v156
	v_lshlrev_b32_e32 v154, 16, v155
	v_and_b32_e32 v155, 0xffff0000, v155
	v_lshlrev_b32_e32 v156, 16, v157
	v_and_b32_e32 v157, 0xffff0000, v157
	v_pk_fma_f32 v[30:31], v[30:31], v[146:147], v[222:223]
	v_pk_fma_f32 v[32:33], v[32:33], v[148:149], v[154:155]
	v_pk_fma_f32 v[26:27], v[26:27], v[150:151], v[224:225]
	v_pk_fma_f32 v[28:29], v[28:29], v[152:153], v[156:157]
	v_cvt_pk_bf16_f32 v222, v30, v31
	v_cvt_pk_bf16_f32 v223, v32, v33
	v_cvt_pk_bf16_f32 v224, v26, v27
	v_cvt_pk_bf16_f32 v225, v28, v29
	global_store_dwordx4 v[216:217], v[222:225], off
	v_pk_mul_f32 v[226:227], v[30:31], v[30:31]
	v_pk_fma_f32 v[226:227], v[32:33], v[32:33], v[226:227]
	v_pk_fma_f32 v[226:227], v[26:27], v[26:27], v[226:227]
	v_pk_fma_f32 v[226:227], v[28:29], v[28:29], v[226:227]
	v_pk_mul_f32 v[30:31], v[30:31], v[208:209]
	v_pk_mul_f32 v[32:33], v[32:33], v[210:211]
	v_pk_mul_f32 v[26:27], v[26:27], v[212:213]
	v_pk_mul_f32 v[28:29], v[28:29], v[214:215]
	v_cvt_pk_bf16_f32 v154, v30, v31
	v_cvt_pk_bf16_f32 v155, v32, v33
	v_cvt_pk_bf16_f32 v156, v26, v27
	v_cvt_pk_bf16_f32 v157, v28, v29
	global_store_dwordx4 v[218:219], v[154:157], off
	s_waitcnt vmcnt(8)
	v_lshlrev_b32_e32 v222, 16, v158
	v_and_b32_e32 v223, 0xffff0000, v158
	v_lshlrev_b32_e32 v224, 16, v160
	v_and_b32_e32 v225, 0xffff0000, v160
	v_lshlrev_b32_e32 v158, 16, v159
	v_and_b32_e32 v159, 0xffff0000, v159
	v_lshlrev_b32_e32 v160, 16, v161
	v_and_b32_e32 v161, 0xffff0000, v161
	v_pk_fma_f32 v[22:23], v[22:23], v[138:139], v[222:223]
	v_pk_fma_f32 v[24:25], v[24:25], v[140:141], v[158:159]
	v_pk_fma_f32 v[14:15], v[14:15], v[142:143], v[224:225]
	v_pk_fma_f32 v[16:17], v[16:17], v[144:145], v[160:161]
	v_cvt_pk_bf16_f32 v222, v22, v23
	v_cvt_pk_bf16_f32 v223, v24, v25
	v_cvt_pk_bf16_f32 v224, v14, v15
	v_cvt_pk_bf16_f32 v225, v16, v17
	global_store_dwordx4 v[216:217], v[222:225], off offset:256
	v_pk_fma_f32 v[226:227], v[22:23], v[22:23], v[226:227]
	v_pk_fma_f32 v[226:227], v[24:25], v[24:25], v[226:227]
	v_pk_fma_f32 v[226:227], v[14:15], v[14:15], v[226:227]
	v_pk_fma_f32 v[226:227], v[16:17], v[16:17], v[226:227]
	v_pk_mul_f32 v[22:23], v[22:23], v[200:201]
	v_pk_mul_f32 v[24:25], v[24:25], v[202:203]
	v_pk_mul_f32 v[14:15], v[14:15], v[204:205]
	v_pk_mul_f32 v[16:17], v[16:17], v[206:207]
	v_cvt_pk_bf16_f32 v158, v22, v23
	v_cvt_pk_bf16_f32 v159, v24, v25
	v_cvt_pk_bf16_f32 v160, v14, v15
	v_cvt_pk_bf16_f32 v161, v16, v17
	global_store_dwordx4 v[218:219], v[158:161], off offset:256
	v_add_f32_e32 v228, v226, v227
	v_lshl_add_u64 v[216:217], v[216:217], 0, s[52:53]
	v_lshl_add_u64 v[218:219], v[218:219], 0, s[52:53]
	global_load_dwordx4 v[154:157], v[220:221], off
	global_load_dwordx4 v[158:161], v[220:221], off offset:256
	v_lshl_add_u64 v[220:221], v[220:221], 0, s[52:53]
	s_waitcnt vmcnt(11)
	v_lshlrev_b32_e32 v222, 16, v162
	v_and_b32_e32 v223, 0xffff0000, v162
	v_lshlrev_b32_e32 v224, 16, v164
	v_and_b32_e32 v225, 0xffff0000, v164
	v_lshlrev_b32_e32 v162, 16, v163
	v_and_b32_e32 v163, 0xffff0000, v163
	v_lshlrev_b32_e32 v164, 16, v165
	v_and_b32_e32 v165, 0xffff0000, v165
	v_pk_fma_f32 v[18:19], v[18:19], v[146:147], v[222:223]
	v_pk_fma_f32 v[20:21], v[20:21], v[148:149], v[162:163]
	v_pk_fma_f32 v[10:11], v[10:11], v[150:151], v[224:225]
	v_pk_fma_f32 v[12:13], v[12:13], v[152:153], v[164:165]
	v_cvt_pk_bf16_f32 v222, v18, v19
	v_cvt_pk_bf16_f32 v223, v20, v21
	v_cvt_pk_bf16_f32 v224, v10, v11
	v_cvt_pk_bf16_f32 v225, v12, v13
	global_store_dwordx4 v[216:217], v[222:225], off
	v_pk_mul_f32 v[226:227], v[18:19], v[18:19]
	v_pk_fma_f32 v[226:227], v[20:21], v[20:21], v[226:227]
	v_pk_fma_f32 v[226:227], v[10:11], v[10:11], v[226:227]
	v_pk_fma_f32 v[226:227], v[12:13], v[12:13], v[226:227]
	v_pk_mul_f32 v[18:19], v[18:19], v[208:209]
	v_pk_mul_f32 v[20:21], v[20:21], v[210:211]
	v_pk_mul_f32 v[10:11], v[10:11], v[212:213]
	v_pk_mul_f32 v[12:13], v[12:13], v[214:215]
	v_cvt_pk_bf16_f32 v162, v18, v19
	v_cvt_pk_bf16_f32 v163, v20, v21
	v_cvt_pk_bf16_f32 v164, v10, v11
	v_cvt_pk_bf16_f32 v165, v12, v13
	global_store_dwordx4 v[218:219], v[162:165], off
	s_waitcnt vmcnt(12)
	v_lshlrev_b32_e32 v222, 16, v166
	v_and_b32_e32 v223, 0xffff0000, v166
	v_lshlrev_b32_e32 v224, 16, v168
	v_and_b32_e32 v225, 0xffff0000, v168
	v_lshlrev_b32_e32 v166, 16, v167
	v_and_b32_e32 v167, 0xffff0000, v167
	v_lshlrev_b32_e32 v168, 16, v169
	v_and_b32_e32 v169, 0xffff0000, v169
	v_pk_fma_f32 v[6:7], v[6:7], v[138:139], v[222:223]
	v_pk_fma_f32 v[8:9], v[8:9], v[140:141], v[166:167]
	v_pk_fma_f32 v[2:3], v[2:3], v[142:143], v[224:225]
	v_pk_fma_f32 v[4:5], v[4:5], v[144:145], v[168:169]
	v_cvt_pk_bf16_f32 v222, v6, v7
	v_cvt_pk_bf16_f32 v223, v8, v9
	v_cvt_pk_bf16_f32 v224, v2, v3
	v_cvt_pk_bf16_f32 v225, v4, v5
	global_store_dwordx4 v[216:217], v[222:225], off offset:256
	v_pk_fma_f32 v[226:227], v[6:7], v[6:7], v[226:227]
	v_pk_fma_f32 v[226:227], v[8:9], v[8:9], v[226:227]
	v_pk_fma_f32 v[226:227], v[2:3], v[2:3], v[226:227]
	v_pk_fma_f32 v[226:227], v[4:5], v[4:5], v[226:227]
	v_pk_mul_f32 v[6:7], v[6:7], v[200:201]
	v_pk_mul_f32 v[8:9], v[8:9], v[202:203]
	v_pk_mul_f32 v[2:3], v[2:3], v[204:205]
	v_pk_mul_f32 v[4:5], v[4:5], v[206:207]
	v_cvt_pk_bf16_f32 v166, v6, v7
	v_cvt_pk_bf16_f32 v167, v8, v9
	v_cvt_pk_bf16_f32 v168, v2, v3
	v_cvt_pk_bf16_f32 v169, v4, v5
	global_store_dwordx4 v[218:219], v[166:169], off offset:256
	v_add_f32_e32 v229, v226, v227
	v_lshl_add_u64 v[216:217], v[216:217], 0, s[52:53]
	v_lshl_add_u64 v[218:219], v[218:219], 0, s[52:53]
	global_load_dwordx4 v[162:165], v[220:221], off
	global_load_dwordx4 v[166:169], v[220:221], off offset:256
	v_lshl_add_u64 v[220:221], v[220:221], 0, s[52:53]
	s_waitcnt vmcnt(15)
	v_lshlrev_b32_e32 v222, 16, v170
	v_and_b32_e32 v223, 0xffff0000, v170
	v_lshlrev_b32_e32 v224, 16, v172
	v_and_b32_e32 v225, 0xffff0000, v172
	v_lshlrev_b32_e32 v170, 16, v171
	v_and_b32_e32 v171, 0xffff0000, v171
	v_lshlrev_b32_e32 v172, 16, v173
	v_and_b32_e32 v173, 0xffff0000, v173
	v_pk_fma_f32 v[126:127], v[126:127], v[146:147], v[222:223]
	v_pk_fma_f32 v[128:129], v[128:129], v[148:149], v[170:171]
	v_pk_fma_f32 v[122:123], v[122:123], v[150:151], v[224:225]
	v_pk_fma_f32 v[124:125], v[124:125], v[152:153], v[172:173]
	v_cvt_pk_bf16_f32 v222, v126, v127
	v_cvt_pk_bf16_f32 v223, v128, v129
	v_cvt_pk_bf16_f32 v224, v122, v123
	v_cvt_pk_bf16_f32 v225, v124, v125
	global_store_dwordx4 v[216:217], v[222:225], off
	v_pk_mul_f32 v[226:227], v[126:127], v[126:127]
	v_pk_fma_f32 v[226:227], v[128:129], v[128:129], v[226:227]
	v_pk_fma_f32 v[226:227], v[122:123], v[122:123], v[226:227]
	v_pk_fma_f32 v[226:227], v[124:125], v[124:125], v[226:227]
	v_pk_mul_f32 v[126:127], v[126:127], v[208:209]
	v_pk_mul_f32 v[128:129], v[128:129], v[210:211]
	v_pk_mul_f32 v[122:123], v[122:123], v[212:213]
	v_pk_mul_f32 v[124:125], v[124:125], v[214:215]
	v_cvt_pk_bf16_f32 v170, v126, v127
	v_cvt_pk_bf16_f32 v171, v128, v129
	v_cvt_pk_bf16_f32 v172, v122, v123
	v_cvt_pk_bf16_f32 v173, v124, v125
	global_store_dwordx4 v[218:219], v[170:173], off
	s_waitcnt vmcnt(16)
	v_lshlrev_b32_e32 v222, 16, v174
	v_and_b32_e32 v223, 0xffff0000, v174
	v_lshlrev_b32_e32 v224, 16, v176
	v_and_b32_e32 v225, 0xffff0000, v176
	v_lshlrev_b32_e32 v174, 16, v175
	v_and_b32_e32 v175, 0xffff0000, v175
	v_lshlrev_b32_e32 v176, 16, v177
	v_and_b32_e32 v177, 0xffff0000, v177
	v_pk_fma_f32 v[118:119], v[118:119], v[138:139], v[222:223]
	v_pk_fma_f32 v[120:121], v[120:121], v[140:141], v[174:175]
	v_pk_fma_f32 v[114:115], v[114:115], v[142:143], v[224:225]
	v_pk_fma_f32 v[116:117], v[116:117], v[144:145], v[176:177]
	v_cvt_pk_bf16_f32 v222, v118, v119
	v_cvt_pk_bf16_f32 v223, v120, v121
	v_cvt_pk_bf16_f32 v224, v114, v115
	v_cvt_pk_bf16_f32 v225, v116, v117
	global_store_dwordx4 v[216:217], v[222:225], off offset:256
	v_pk_fma_f32 v[226:227], v[118:119], v[118:119], v[226:227]
	v_pk_fma_f32 v[226:227], v[120:121], v[120:121], v[226:227]
	v_pk_fma_f32 v[226:227], v[114:115], v[114:115], v[226:227]
	v_pk_fma_f32 v[226:227], v[116:117], v[116:117], v[226:227]
	v_pk_mul_f32 v[118:119], v[118:119], v[200:201]
	v_pk_mul_f32 v[120:121], v[120:121], v[202:203]
	v_pk_mul_f32 v[114:115], v[114:115], v[204:205]
	v_pk_mul_f32 v[116:117], v[116:117], v[206:207]
	v_cvt_pk_bf16_f32 v174, v118, v119
	v_cvt_pk_bf16_f32 v175, v120, v121
	v_cvt_pk_bf16_f32 v176, v114, v115
	v_cvt_pk_bf16_f32 v177, v116, v117
	global_store_dwordx4 v[218:219], v[174:177], off offset:256
	v_add_f32_e32 v22, v226, v227
	v_lshl_add_u64 v[216:217], v[216:217], 0, s[52:53]
	v_lshl_add_u64 v[218:219], v[218:219], 0, s[52:53]
	global_load_dwordx4 v[170:173], v[220:221], off
	global_load_dwordx4 v[174:177], v[220:221], off offset:256
	v_lshl_add_u64 v[220:221], v[220:221], 0, s[52:53]
	s_waitcnt vmcnt(19)
	v_lshlrev_b32_e32 v222, 16, v130
	v_and_b32_e32 v223, 0xffff0000, v130
	v_lshlrev_b32_e32 v224, 16, v132
	v_and_b32_e32 v225, 0xffff0000, v132
	v_lshlrev_b32_e32 v130, 16, v131
	v_and_b32_e32 v131, 0xffff0000, v131
	v_lshlrev_b32_e32 v132, 16, v133
	v_and_b32_e32 v133, 0xffff0000, v133
	v_pk_fma_f32 v[110:111], v[110:111], v[146:147], v[222:223]
	v_pk_fma_f32 v[112:113], v[112:113], v[148:149], v[130:131]
	v_pk_fma_f32 v[106:107], v[106:107], v[150:151], v[224:225]
	v_pk_fma_f32 v[108:109], v[108:109], v[152:153], v[132:133]
	v_cvt_pk_bf16_f32 v222, v110, v111
	v_cvt_pk_bf16_f32 v223, v112, v113
	v_cvt_pk_bf16_f32 v224, v106, v107
	v_cvt_pk_bf16_f32 v225, v108, v109
	global_store_dwordx4 v[216:217], v[222:225], off
	v_pk_mul_f32 v[226:227], v[110:111], v[110:111]
	v_pk_fma_f32 v[226:227], v[112:113], v[112:113], v[226:227]
	v_pk_fma_f32 v[226:227], v[106:107], v[106:107], v[226:227]
	v_pk_fma_f32 v[226:227], v[108:109], v[108:109], v[226:227]
	v_pk_mul_f32 v[110:111], v[110:111], v[208:209]
	v_pk_mul_f32 v[112:113], v[112:113], v[210:211]
	v_pk_mul_f32 v[106:107], v[106:107], v[212:213]
	v_pk_mul_f32 v[108:109], v[108:109], v[214:215]
	v_cvt_pk_bf16_f32 v130, v110, v111
	v_cvt_pk_bf16_f32 v131, v112, v113
	v_cvt_pk_bf16_f32 v132, v106, v107
	v_cvt_pk_bf16_f32 v133, v108, v109
	global_store_dwordx4 v[218:219], v[130:133], off
	s_waitcnt vmcnt(20)
	v_lshlrev_b32_e32 v222, 16, v134
	v_and_b32_e32 v223, 0xffff0000, v134
	v_lshlrev_b32_e32 v224, 16, v136
	v_and_b32_e32 v225, 0xffff0000, v136
	v_lshlrev_b32_e32 v134, 16, v135
	v_and_b32_e32 v135, 0xffff0000, v135
	v_lshlrev_b32_e32 v136, 16, v137
	v_and_b32_e32 v137, 0xffff0000, v137
	v_pk_fma_f32 v[102:103], v[102:103], v[138:139], v[222:223]
	v_pk_fma_f32 v[104:105], v[104:105], v[140:141], v[134:135]
	v_pk_fma_f32 v[98:99], v[98:99], v[142:143], v[224:225]
	v_pk_fma_f32 v[100:101], v[100:101], v[144:145], v[136:137]
	v_cvt_pk_bf16_f32 v222, v102, v103
	v_cvt_pk_bf16_f32 v223, v104, v105
	v_cvt_pk_bf16_f32 v224, v98, v99
	v_cvt_pk_bf16_f32 v225, v100, v101
	global_store_dwordx4 v[216:217], v[222:225], off offset:256
	v_pk_fma_f32 v[226:227], v[102:103], v[102:103], v[226:227]
	v_pk_fma_f32 v[226:227], v[104:105], v[104:105], v[226:227]
	v_pk_fma_f32 v[226:227], v[98:99], v[98:99], v[226:227]
	v_pk_fma_f32 v[226:227], v[100:101], v[100:101], v[226:227]
	v_pk_mul_f32 v[102:103], v[102:103], v[200:201]
	v_pk_mul_f32 v[104:105], v[104:105], v[202:203]
	v_pk_mul_f32 v[98:99], v[98:99], v[204:205]
	v_pk_mul_f32 v[100:101], v[100:101], v[206:207]
	v_cvt_pk_bf16_f32 v134, v102, v103
	v_cvt_pk_bf16_f32 v135, v104, v105
	v_cvt_pk_bf16_f32 v136, v98, v99
	v_cvt_pk_bf16_f32 v137, v100, v101
	global_store_dwordx4 v[218:219], v[134:137], off offset:256
	v_add_f32_e32 v23, v226, v227
	v_lshl_add_u64 v[216:217], v[216:217], 0, s[14:15]
	v_lshl_add_u64 v[218:219], v[218:219], 0, s[14:15]
	global_load_dwordx4 v[130:133], v[220:221], off
	global_load_dwordx4 v[134:137], v[220:221], off offset:256
	s_waitcnt vmcnt(19)
	v_lshlrev_b32_e32 v222, 16, v154
	v_and_b32_e32 v223, 0xffff0000, v154
	v_lshlrev_b32_e32 v224, 16, v156
	v_and_b32_e32 v225, 0xffff0000, v156
	v_lshlrev_b32_e32 v154, 16, v155
	v_and_b32_e32 v155, 0xffff0000, v155
	v_lshlrev_b32_e32 v156, 16, v157
	v_and_b32_e32 v157, 0xffff0000, v157
	v_pk_fma_f32 v[94:95], v[94:95], v[146:147], v[222:223]
	v_pk_fma_f32 v[96:97], v[96:97], v[148:149], v[154:155]
	v_pk_fma_f32 v[90:91], v[90:91], v[150:151], v[224:225]
	v_pk_fma_f32 v[92:93], v[92:93], v[152:153], v[156:157]
	v_cvt_pk_bf16_f32 v222, v94, v95
	v_cvt_pk_bf16_f32 v223, v96, v97
	v_cvt_pk_bf16_f32 v224, v90, v91
	v_cvt_pk_bf16_f32 v225, v92, v93
	global_store_dwordx4 v[216:217], v[222:225], off
	v_pk_mul_f32 v[226:227], v[94:95], v[94:95]
	v_pk_fma_f32 v[226:227], v[96:97], v[96:97], v[226:227]
	v_pk_fma_f32 v[226:227], v[90:91], v[90:91], v[226:227]
	v_pk_fma_f32 v[226:227], v[92:93], v[92:93], v[226:227]
	v_pk_mul_f32 v[94:95], v[94:95], v[208:209]
	v_pk_mul_f32 v[96:97], v[96:97], v[210:211]
	v_pk_mul_f32 v[90:91], v[90:91], v[212:213]
	v_pk_mul_f32 v[92:93], v[92:93], v[214:215]
	v_cvt_pk_bf16_f32 v154, v94, v95
	v_cvt_pk_bf16_f32 v155, v96, v97
	v_cvt_pk_bf16_f32 v156, v90, v91
	v_cvt_pk_bf16_f32 v157, v92, v93
	global_store_dwordx4 v[218:219], v[154:157], off
	s_waitcnt vmcnt(20)
	v_lshlrev_b32_e32 v222, 16, v158
	v_and_b32_e32 v223, 0xffff0000, v158
	v_lshlrev_b32_e32 v224, 16, v160
	v_and_b32_e32 v225, 0xffff0000, v160
	v_lshlrev_b32_e32 v158, 16, v159
	v_and_b32_e32 v159, 0xffff0000, v159
	v_lshlrev_b32_e32 v160, 16, v161
	v_and_b32_e32 v161, 0xffff0000, v161
	v_pk_fma_f32 v[86:87], v[86:87], v[138:139], v[222:223]
	v_pk_fma_f32 v[88:89], v[88:89], v[140:141], v[158:159]
	v_pk_fma_f32 v[82:83], v[82:83], v[142:143], v[224:225]
	v_pk_fma_f32 v[84:85], v[84:85], v[144:145], v[160:161]
	v_cvt_pk_bf16_f32 v222, v86, v87
	v_cvt_pk_bf16_f32 v223, v88, v89
	v_cvt_pk_bf16_f32 v224, v82, v83
	v_cvt_pk_bf16_f32 v225, v84, v85
	global_store_dwordx4 v[216:217], v[222:225], off offset:256
	v_pk_fma_f32 v[226:227], v[86:87], v[86:87], v[226:227]
	v_pk_fma_f32 v[226:227], v[88:89], v[88:89], v[226:227]
	v_pk_fma_f32 v[226:227], v[82:83], v[82:83], v[226:227]
	v_pk_fma_f32 v[226:227], v[84:85], v[84:85], v[226:227]
	v_pk_mul_f32 v[86:87], v[86:87], v[200:201]
	v_pk_mul_f32 v[88:89], v[88:89], v[202:203]
	v_pk_mul_f32 v[82:83], v[82:83], v[204:205]
	v_pk_mul_f32 v[84:85], v[84:85], v[206:207]
	v_cvt_pk_bf16_f32 v158, v86, v87
	v_cvt_pk_bf16_f32 v159, v88, v89
	v_cvt_pk_bf16_f32 v160, v82, v83
	v_cvt_pk_bf16_f32 v161, v84, v85
	global_store_dwordx4 v[218:219], v[158:161], off offset:256
	v_add_f32_e32 v24, v226, v227
	v_lshl_add_u64 v[216:217], v[216:217], 0, s[52:53]
	v_lshl_add_u64 v[218:219], v[218:219], 0, s[52:53]
	s_waitcnt vmcnt(17)
	v_lshlrev_b32_e32 v222, 16, v162
	v_and_b32_e32 v223, 0xffff0000, v162
	v_lshlrev_b32_e32 v224, 16, v164
	v_and_b32_e32 v225, 0xffff0000, v164
	v_lshlrev_b32_e32 v162, 16, v163
	v_and_b32_e32 v163, 0xffff0000, v163
	v_lshlrev_b32_e32 v164, 16, v165
	v_and_b32_e32 v165, 0xffff0000, v165
	v_pk_fma_f32 v[78:79], v[78:79], v[146:147], v[222:223]
	v_pk_fma_f32 v[80:81], v[80:81], v[148:149], v[162:163]
	v_pk_fma_f32 v[74:75], v[74:75], v[150:151], v[224:225]
	v_pk_fma_f32 v[76:77], v[76:77], v[152:153], v[164:165]
	v_cvt_pk_bf16_f32 v222, v78, v79
	v_cvt_pk_bf16_f32 v223, v80, v81
	v_cvt_pk_bf16_f32 v224, v74, v75
	v_cvt_pk_bf16_f32 v225, v76, v77
	global_store_dwordx4 v[216:217], v[222:225], off
	v_pk_mul_f32 v[226:227], v[78:79], v[78:79]
	v_pk_fma_f32 v[226:227], v[80:81], v[80:81], v[226:227]
	v_pk_fma_f32 v[226:227], v[74:75], v[74:75], v[226:227]
	v_pk_fma_f32 v[226:227], v[76:77], v[76:77], v[226:227]
	v_pk_mul_f32 v[78:79], v[78:79], v[208:209]
	v_pk_mul_f32 v[80:81], v[80:81], v[210:211]
	v_pk_mul_f32 v[74:75], v[74:75], v[212:213]
	v_pk_mul_f32 v[76:77], v[76:77], v[214:215]
	v_cvt_pk_bf16_f32 v162, v78, v79
	v_cvt_pk_bf16_f32 v163, v80, v81
	v_cvt_pk_bf16_f32 v164, v74, v75
	v_cvt_pk_bf16_f32 v165, v76, v77
	global_store_dwordx4 v[218:219], v[162:165], off
	s_waitcnt vmcnt(18)
	v_lshlrev_b32_e32 v222, 16, v166
	v_and_b32_e32 v223, 0xffff0000, v166
	v_lshlrev_b32_e32 v224, 16, v168
	v_and_b32_e32 v225, 0xffff0000, v168
	v_lshlrev_b32_e32 v166, 16, v167
	v_and_b32_e32 v167, 0xffff0000, v167
	v_lshlrev_b32_e32 v168, 16, v169
	v_and_b32_e32 v169, 0xffff0000, v169
	v_pk_fma_f32 v[70:71], v[70:71], v[138:139], v[222:223]
	v_pk_fma_f32 v[72:73], v[72:73], v[140:141], v[166:167]
	v_pk_fma_f32 v[66:67], v[66:67], v[142:143], v[224:225]
	v_pk_fma_f32 v[68:69], v[68:69], v[144:145], v[168:169]
	v_cvt_pk_bf16_f32 v222, v70, v71
	v_cvt_pk_bf16_f32 v223, v72, v73
	v_cvt_pk_bf16_f32 v224, v66, v67
	v_cvt_pk_bf16_f32 v225, v68, v69
	global_store_dwordx4 v[216:217], v[222:225], off offset:256
	v_pk_fma_f32 v[226:227], v[70:71], v[70:71], v[226:227]
	v_pk_fma_f32 v[226:227], v[72:73], v[72:73], v[226:227]
	v_pk_fma_f32 v[226:227], v[66:67], v[66:67], v[226:227]
	v_pk_fma_f32 v[226:227], v[68:69], v[68:69], v[226:227]
	v_pk_mul_f32 v[70:71], v[70:71], v[200:201]
	v_pk_mul_f32 v[72:73], v[72:73], v[202:203]
	v_pk_mul_f32 v[66:67], v[66:67], v[204:205]
	v_pk_mul_f32 v[68:69], v[68:69], v[206:207]
	v_cvt_pk_bf16_f32 v166, v70, v71
	v_cvt_pk_bf16_f32 v167, v72, v73
	v_cvt_pk_bf16_f32 v168, v66, v67
	v_cvt_pk_bf16_f32 v169, v68, v69
	global_store_dwordx4 v[218:219], v[166:169], off offset:256
	v_add_f32_e32 v25, v226, v227
	v_lshl_add_u64 v[216:217], v[216:217], 0, s[52:53]
	v_lshl_add_u64 v[218:219], v[218:219], 0, s[52:53]
	s_waitcnt vmcnt(15)
	v_lshlrev_b32_e32 v222, 16, v170
	v_and_b32_e32 v223, 0xffff0000, v170
	v_lshlrev_b32_e32 v224, 16, v172
	v_and_b32_e32 v225, 0xffff0000, v172
	v_lshlrev_b32_e32 v170, 16, v171
	v_and_b32_e32 v171, 0xffff0000, v171
	v_lshlrev_b32_e32 v172, 16, v173
	v_and_b32_e32 v173, 0xffff0000, v173
	v_pk_fma_f32 v[62:63], v[62:63], v[146:147], v[222:223]
	v_pk_fma_f32 v[64:65], v[64:65], v[148:149], v[170:171]
	v_pk_fma_f32 v[58:59], v[58:59], v[150:151], v[224:225]
	v_pk_fma_f32 v[60:61], v[60:61], v[152:153], v[172:173]
	v_cvt_pk_bf16_f32 v222, v62, v63
	v_cvt_pk_bf16_f32 v223, v64, v65
	v_cvt_pk_bf16_f32 v224, v58, v59
	v_cvt_pk_bf16_f32 v225, v60, v61
	global_store_dwordx4 v[216:217], v[222:225], off
	v_pk_mul_f32 v[226:227], v[62:63], v[62:63]
	v_pk_fma_f32 v[226:227], v[64:65], v[64:65], v[226:227]
	v_pk_fma_f32 v[226:227], v[58:59], v[58:59], v[226:227]
	v_pk_fma_f32 v[226:227], v[60:61], v[60:61], v[226:227]
	v_pk_mul_f32 v[62:63], v[62:63], v[208:209]
	v_pk_mul_f32 v[64:65], v[64:65], v[210:211]
	v_pk_mul_f32 v[58:59], v[58:59], v[212:213]
	v_pk_mul_f32 v[60:61], v[60:61], v[214:215]
	v_cvt_pk_bf16_f32 v170, v62, v63
	v_cvt_pk_bf16_f32 v171, v64, v65
	v_cvt_pk_bf16_f32 v172, v58, v59
	v_cvt_pk_bf16_f32 v173, v60, v61
	global_store_dwordx4 v[218:219], v[170:173], off
	s_waitcnt vmcnt(16)
	v_lshlrev_b32_e32 v222, 16, v174
	v_and_b32_e32 v223, 0xffff0000, v174
	v_lshlrev_b32_e32 v224, 16, v176
	v_and_b32_e32 v225, 0xffff0000, v176
	v_lshlrev_b32_e32 v174, 16, v175
	v_and_b32_e32 v175, 0xffff0000, v175
	v_lshlrev_b32_e32 v176, 16, v177
	v_and_b32_e32 v177, 0xffff0000, v177
	v_pk_fma_f32 v[54:55], v[54:55], v[138:139], v[222:223]
	v_pk_fma_f32 v[56:57], v[56:57], v[140:141], v[174:175]
	v_pk_fma_f32 v[50:51], v[50:51], v[142:143], v[224:225]
	v_pk_fma_f32 v[52:53], v[52:53], v[144:145], v[176:177]
	v_cvt_pk_bf16_f32 v222, v54, v55
	v_cvt_pk_bf16_f32 v223, v56, v57
	v_cvt_pk_bf16_f32 v224, v50, v51
	v_cvt_pk_bf16_f32 v225, v52, v53
	global_store_dwordx4 v[216:217], v[222:225], off offset:256
	v_pk_fma_f32 v[226:227], v[54:55], v[54:55], v[226:227]
	v_pk_fma_f32 v[226:227], v[56:57], v[56:57], v[226:227]
	v_pk_fma_f32 v[226:227], v[50:51], v[50:51], v[226:227]
	v_pk_fma_f32 v[226:227], v[52:53], v[52:53], v[226:227]
	v_pk_mul_f32 v[54:55], v[54:55], v[200:201]
	v_pk_mul_f32 v[56:57], v[56:57], v[202:203]
	v_pk_mul_f32 v[50:51], v[50:51], v[204:205]
	v_pk_mul_f32 v[52:53], v[52:53], v[206:207]
	v_cvt_pk_bf16_f32 v174, v54, v55
	v_cvt_pk_bf16_f32 v175, v56, v57
	v_cvt_pk_bf16_f32 v176, v50, v51
	v_cvt_pk_bf16_f32 v177, v52, v53
	global_store_dwordx4 v[218:219], v[174:177], off offset:256
	v_add_f32_e32 v26, v226, v227
	v_lshl_add_u64 v[216:217], v[216:217], 0, s[52:53]
	v_lshl_add_u64 v[218:219], v[218:219], 0, s[52:53]
	s_waitcnt vmcnt(13)
	v_lshlrev_b32_e32 v222, 16, v130
	v_and_b32_e32 v223, 0xffff0000, v130
	v_lshlrev_b32_e32 v224, 16, v132
	v_and_b32_e32 v225, 0xffff0000, v132
	v_lshlrev_b32_e32 v130, 16, v131
	v_and_b32_e32 v131, 0xffff0000, v131
	v_lshlrev_b32_e32 v132, 16, v133
	v_and_b32_e32 v133, 0xffff0000, v133
	v_pk_fma_f32 v[46:47], v[46:47], v[146:147], v[222:223]
	v_pk_fma_f32 v[48:49], v[48:49], v[148:149], v[130:131]
	v_pk_fma_f32 v[42:43], v[42:43], v[150:151], v[224:225]
	v_pk_fma_f32 v[44:45], v[44:45], v[152:153], v[132:133]
	v_cvt_pk_bf16_f32 v222, v46, v47
	v_cvt_pk_bf16_f32 v223, v48, v49
	v_cvt_pk_bf16_f32 v224, v42, v43
	v_cvt_pk_bf16_f32 v225, v44, v45
	global_store_dwordx4 v[216:217], v[222:225], off
	v_pk_mul_f32 v[226:227], v[46:47], v[46:47]
	v_pk_fma_f32 v[226:227], v[48:49], v[48:49], v[226:227]
	v_pk_fma_f32 v[226:227], v[42:43], v[42:43], v[226:227]
	v_pk_fma_f32 v[226:227], v[44:45], v[44:45], v[226:227]
	v_pk_mul_f32 v[46:47], v[46:47], v[208:209]
	v_pk_mul_f32 v[48:49], v[48:49], v[210:211]
	v_pk_mul_f32 v[42:43], v[42:43], v[212:213]
	v_pk_mul_f32 v[44:45], v[44:45], v[214:215]
	v_cvt_pk_bf16_f32 v130, v46, v47
	v_cvt_pk_bf16_f32 v131, v48, v49
	v_cvt_pk_bf16_f32 v132, v42, v43
	v_cvt_pk_bf16_f32 v133, v44, v45
	global_store_dwordx4 v[218:219], v[130:133], off
	s_waitcnt vmcnt(14)
	v_lshlrev_b32_e32 v222, 16, v134
	v_and_b32_e32 v223, 0xffff0000, v134
	v_lshlrev_b32_e32 v224, 16, v136
	v_and_b32_e32 v225, 0xffff0000, v136
	v_lshlrev_b32_e32 v134, 16, v135
	v_and_b32_e32 v135, 0xffff0000, v135
	v_lshlrev_b32_e32 v136, 16, v137
	v_and_b32_e32 v137, 0xffff0000, v137
	v_pk_fma_f32 v[38:39], v[38:39], v[138:139], v[222:223]
	v_pk_fma_f32 v[40:41], v[40:41], v[140:141], v[134:135]
	v_pk_fma_f32 v[34:35], v[34:35], v[142:143], v[224:225]
	v_pk_fma_f32 v[36:37], v[36:37], v[144:145], v[136:137]
	v_cvt_pk_bf16_f32 v222, v38, v39
	v_cvt_pk_bf16_f32 v223, v40, v41
	v_cvt_pk_bf16_f32 v224, v34, v35
	v_cvt_pk_bf16_f32 v225, v36, v37
	global_store_dwordx4 v[216:217], v[222:225], off offset:256
	v_pk_fma_f32 v[226:227], v[38:39], v[38:39], v[226:227]
	v_pk_fma_f32 v[226:227], v[40:41], v[40:41], v[226:227]
	v_pk_fma_f32 v[226:227], v[34:35], v[34:35], v[226:227]
	v_pk_fma_f32 v[226:227], v[36:37], v[36:37], v[226:227]
	v_pk_mul_f32 v[38:39], v[38:39], v[200:201]
	v_pk_mul_f32 v[40:41], v[40:41], v[202:203]
	v_pk_mul_f32 v[34:35], v[34:35], v[204:205]
	v_pk_mul_f32 v[36:37], v[36:37], v[206:207]
	v_cvt_pk_bf16_f32 v134, v38, v39
	v_cvt_pk_bf16_f32 v135, v40, v41
	v_cvt_pk_bf16_f32 v136, v34, v35
	v_cvt_pk_bf16_f32 v137, v36, v37
	global_store_dwordx4 v[218:219], v[134:137], off offset:256
	v_add_f32_e32 v27, v226, v227
	ds_bpermute_b32 v28, v244, v228
	ds_bpermute_b32 v29, v244, v229
	ds_bpermute_b32 v30, v244, v22
	ds_bpermute_b32 v31, v244, v23
	ds_bpermute_b32 v32, v244, v24
	ds_bpermute_b32 v33, v244, v25
	ds_bpermute_b32 v14, v244, v26
	ds_bpermute_b32 v15, v244, v27
	v_readlane_b32 s12, v254, 44
	s_waitcnt lgkmcnt(0)
	v_add_f32_e32 v228, v228, v28
	v_add_f32_e32 v229, v229, v29
	v_add_f32_e32 v22, v22, v30
	v_add_f32_e32 v23, v23, v31
	v_add_f32_e32 v24, v24, v32
	v_add_f32_e32 v25, v25, v33
	v_add_f32_e32 v26, v26, v14
	v_add_f32_e32 v27, v27, v15
	ds_bpermute_b32 v28, v245, v228
	ds_bpermute_b32 v29, v245, v229
	ds_bpermute_b32 v30, v245, v22
	ds_bpermute_b32 v31, v245, v23
	ds_bpermute_b32 v32, v245, v24
	ds_bpermute_b32 v33, v245, v25
	ds_bpermute_b32 v14, v245, v26
	ds_bpermute_b32 v15, v245, v27
	v_lshl_add_u32 v0, v241, 4, s12
	s_waitcnt lgkmcnt(0)
	v_add_f32_e32 v228, v228, v28
	v_add_f32_e32 v229, v229, v29
	v_add_f32_e32 v22, v22, v30
	v_add_f32_e32 v23, v23, v31
	v_add_f32_e32 v24, v24, v32
	v_add_f32_e32 v25, v25, v33
	v_add_f32_e32 v26, v26, v14
	v_add_f32_e32 v27, v27, v15
	s_and_saveexec_b64 s[10:11], s[88:89]
	ds_write_b32 v0, v228
	ds_write_b32 v0, v229 offset:256
	ds_write_b32 v0, v22 offset:512
	ds_write_b32 v0, v23 offset:768
	ds_write_b32 v0, v24 offset:2048
	ds_write_b32 v0, v25 offset:2304
	ds_write_b32 v0, v26 offset:2560
	ds_write_b32 v0, v27 offset:2816
	v_readlane_b32 s72, v253, 57
	v_readlane_b32 s73, v253, 58
	v_readlane_b32 s80, v254, 51
	v_readlane_b32 s81, v254, 52
	v_readlane_b32 s66, v254, 58
	v_readlane_b32 s67, v254, 59
	v_readlane_b32 s54, v253, 59
	v_readlane_b32 s55, v253, 60
	s_branch .LBB0_503
.Lepr_last:
	s_load_dwordx4 s[64:67], s[0:1], 0xb8
	s_lshl_b32 s17, s34, 8
	s_mov_b64 s[52:53], 0x8000
	s_mov_b64 s[14:15], 0x28000
	v_add_u32_e32 v134, s17, v241
	v_ashrrev_i32_e32 v135, 31, v134
	v_lshlrev_b64 v[136:137], 12, v[134:135]
	v_lshl_add_u64 v[136:137], v[220:221], 2, v[136:137]
	v_lshlrev_b64 v[134:135], 11, v[134:135]
	v_lshl_add_u64 v[134:135], v[220:221], 1, v[134:135]
	s_waitcnt lgkmcnt(0)
	s_add_u32 s54, s66, 0xe800000
	s_addc_u32 s55, s67, 0
	v_lshl_add_u64 v[220:221], v[134:135], 0, s[54:55]
	v_lshl_add_u64 v[218:219], v[136:137], 0, s[64:65]
	s_mov_b64 s[10:11], 0x10000
	s_mov_b64 s[12:13], 0x50000
	global_load_dwordx4 v[154:157], v[220:221], off
	global_load_dwordx4 v[158:161], v[220:221], off offset:256
	v_lshl_add_u64 v[220:221], v[220:221], 0, s[52:53]
	global_load_dwordx4 v[162:165], v[220:221], off
	global_load_dwordx4 v[166:169], v[220:221], off offset:256
	v_lshl_add_u64 v[220:221], v[220:221], 0, s[52:53]
	global_load_dwordx4 v[170:173], v[220:221], off
	global_load_dwordx4 v[174:177], v[220:221], off offset:256
	v_lshl_add_u64 v[220:221], v[220:221], 0, s[52:53]
	global_load_dwordx4 v[130:133], v[220:221], off
	global_load_dwordx4 v[134:137], v[220:221], off offset:256
	v_lshl_add_u64 v[220:221], v[220:221], 0, s[14:15]
	s_waitcnt vmcnt(8)
	v_pk_mul_f32 v[146:147], v[146:147], v[192:193]
	v_pk_mul_f32 v[148:149], v[148:149], v[192:193]
	v_pk_mul_f32 v[150:151], v[150:151], v[192:193]
	v_pk_mul_f32 v[152:153], v[152:153], v[192:193]
	v_pk_mul_f32 v[138:139], v[138:139], v[192:193]
	v_pk_mul_f32 v[140:141], v[140:141], v[192:193]
	v_pk_mul_f32 v[142:143], v[142:143], v[192:193]
	v_pk_mul_f32 v[144:145], v[144:145], v[192:193]
	s_waitcnt vmcnt(7)
	v_lshlrev_b32_e32 v222, 16, v154
	v_and_b32_e32 v223, 0xffff0000, v154
	v_lshlrev_b32_e32 v224, 16, v156
	v_and_b32_e32 v225, 0xffff0000, v156
	v_lshlrev_b32_e32 v154, 16, v155
	v_and_b32_e32 v155, 0xffff0000, v155
	v_lshlrev_b32_e32 v156, 16, v157
	v_and_b32_e32 v157, 0xffff0000, v157
	v_pk_fma_f32 v[30:31], v[30:31], v[146:147], v[222:223]
	v_pk_fma_f32 v[32:33], v[32:33], v[148:149], v[154:155]
	v_pk_fma_f32 v[26:27], v[26:27], v[150:151], v[224:225]
	v_pk_fma_f32 v[28:29], v[28:29], v[152:153], v[156:157]
	global_store_dwordx4 v[218:219], v[30:33], off nt
	global_store_dwordx4 v[218:219], v[26:29], off offset:16 nt
	s_waitcnt vmcnt(8)
	v_lshlrev_b32_e32 v222, 16, v158
	v_and_b32_e32 v223, 0xffff0000, v158
	v_lshlrev_b32_e32 v224, 16, v160
	v_and_b32_e32 v225, 0xffff0000, v160
	v_lshlrev_b32_e32 v158, 16, v159
	v_and_b32_e32 v159, 0xffff0000, v159
	v_lshlrev_b32_e32 v160, 16, v161
	v_and_b32_e32 v161, 0xffff0000, v161
	v_pk_fma_f32 v[22:23], v[22:23], v[138:139], v[222:223]
	v_pk_fma_f32 v[24:25], v[24:25], v[140:141], v[158:159]
	v_pk_fma_f32 v[14:15], v[14:15], v[142:143], v[224:225]
	v_pk_fma_f32 v[16:17], v[16:17], v[144:145], v[160:161]
	global_store_dwordx4 v[218:219], v[22:25], off offset:512 nt
	global_store_dwordx4 v[218:219], v[14:17], off offset:528 nt
	v_lshl_add_u64 v[218:219], v[218:219], 0, s[10:11]
	global_load_dwordx4 v[154:157], v[220:221], off
	global_load_dwordx4 v[158:161], v[220:221], off offset:256
	v_lshl_add_u64 v[220:221], v[220:221], 0, s[52:53]
	s_waitcnt vmcnt(11)
	v_lshlrev_b32_e32 v222, 16, v162
	v_and_b32_e32 v223, 0xffff0000, v162
	v_lshlrev_b32_e32 v224, 16, v164
	v_and_b32_e32 v225, 0xffff0000, v164
	v_lshlrev_b32_e32 v162, 16, v163
	v_and_b32_e32 v163, 0xffff0000, v163
	v_lshlrev_b32_e32 v164, 16, v165
	v_and_b32_e32 v165, 0xffff0000, v165
	v_pk_fma_f32 v[18:19], v[18:19], v[146:147], v[222:223]
	v_pk_fma_f32 v[20:21], v[20:21], v[148:149], v[162:163]
	v_pk_fma_f32 v[10:11], v[10:11], v[150:151], v[224:225]
	v_pk_fma_f32 v[12:13], v[12:13], v[152:153], v[164:165]
	global_store_dwordx4 v[218:219], v[18:21], off nt
	global_store_dwordx4 v[218:219], v[10:13], off offset:16 nt
	s_waitcnt vmcnt(12)
	v_lshlrev_b32_e32 v222, 16, v166
	v_and_b32_e32 v223, 0xffff0000, v166
	v_lshlrev_b32_e32 v224, 16, v168
	v_and_b32_e32 v225, 0xffff0000, v168
	v_lshlrev_b32_e32 v166, 16, v167
	v_and_b32_e32 v167, 0xffff0000, v167
	v_lshlrev_b32_e32 v168, 16, v169
	v_and_b32_e32 v169, 0xffff0000, v169
	v_pk_fma_f32 v[6:7], v[6:7], v[138:139], v[222:223]
	v_pk_fma_f32 v[8:9], v[8:9], v[140:141], v[166:167]
	v_pk_fma_f32 v[2:3], v[2:3], v[142:143], v[224:225]
	v_pk_fma_f32 v[4:5], v[4:5], v[144:145], v[168:169]
	global_store_dwordx4 v[218:219], v[6:9], off offset:512 nt
	global_store_dwordx4 v[218:219], v[2:5], off offset:528 nt
	v_lshl_add_u64 v[218:219], v[218:219], 0, s[10:11]
	global_load_dwordx4 v[162:165], v[220:221], off
	global_load_dwordx4 v[166:169], v[220:221], off offset:256
	v_lshl_add_u64 v[220:221], v[220:221], 0, s[52:53]
	s_waitcnt vmcnt(15)
	v_lshlrev_b32_e32 v222, 16, v170
	v_and_b32_e32 v223, 0xffff0000, v170
	v_lshlrev_b32_e32 v224, 16, v172
	v_and_b32_e32 v225, 0xffff0000, v172
	v_lshlrev_b32_e32 v170, 16, v171
	v_and_b32_e32 v171, 0xffff0000, v171
	v_lshlrev_b32_e32 v172, 16, v173
	v_and_b32_e32 v173, 0xffff0000, v173
	v_pk_fma_f32 v[126:127], v[126:127], v[146:147], v[222:223]
	v_pk_fma_f32 v[128:129], v[128:129], v[148:149], v[170:171]
	v_pk_fma_f32 v[122:123], v[122:123], v[150:151], v[224:225]
	v_pk_fma_f32 v[124:125], v[124:125], v[152:153], v[172:173]
	global_store_dwordx4 v[218:219], v[126:129], off nt
	global_store_dwordx4 v[218:219], v[122:125], off offset:16 nt
	s_waitcnt vmcnt(16)
	v_lshlrev_b32_e32 v222, 16, v174
	v_and_b32_e32 v223, 0xffff0000, v174
	v_lshlrev_b32_e32 v224, 16, v176
	v_and_b32_e32 v225, 0xffff0000, v176
	v_lshlrev_b32_e32 v174, 16, v175
	v_and_b32_e32 v175, 0xffff0000, v175
	v_lshlrev_b32_e32 v176, 16, v177
	v_and_b32_e32 v177, 0xffff0000, v177
	v_pk_fma_f32 v[118:119], v[118:119], v[138:139], v[222:223]
	v_pk_fma_f32 v[120:121], v[120:121], v[140:141], v[174:175]
	v_pk_fma_f32 v[114:115], v[114:115], v[142:143], v[224:225]
	v_pk_fma_f32 v[116:117], v[116:117], v[144:145], v[176:177]
	global_store_dwordx4 v[218:219], v[118:121], off offset:512 nt
	global_store_dwordx4 v[218:219], v[114:117], off offset:528 nt
	v_lshl_add_u64 v[218:219], v[218:219], 0, s[10:11]
	global_load_dwordx4 v[170:173], v[220:221], off
	global_load_dwordx4 v[174:177], v[220:221], off offset:256
	v_lshl_add_u64 v[220:221], v[220:221], 0, s[52:53]
	s_waitcnt vmcnt(19)
	v_lshlrev_b32_e32 v222, 16, v130
	v_and_b32_e32 v223, 0xffff0000, v130
	v_lshlrev_b32_e32 v224, 16, v132
	v_and_b32_e32 v225, 0xffff0000, v132
	v_lshlrev_b32_e32 v130, 16, v131
	v_and_b32_e32 v131, 0xffff0000, v131
	v_lshlrev_b32_e32 v132, 16, v133
	v_and_b32_e32 v133, 0xffff0000, v133
	v_pk_fma_f32 v[110:111], v[110:111], v[146:147], v[222:223]
	v_pk_fma_f32 v[112:113], v[112:113], v[148:149], v[130:131]
	v_pk_fma_f32 v[106:107], v[106:107], v[150:151], v[224:225]
	v_pk_fma_f32 v[108:109], v[108:109], v[152:153], v[132:133]
	global_store_dwordx4 v[218:219], v[110:113], off nt
	global_store_dwordx4 v[218:219], v[106:109], off offset:16 nt
	s_waitcnt vmcnt(20)
	v_lshlrev_b32_e32 v222, 16, v134
	v_and_b32_e32 v223, 0xffff0000, v134
	v_lshlrev_b32_e32 v224, 16, v136
	v_and_b32_e32 v225, 0xffff0000, v136
	v_lshlrev_b32_e32 v134, 16, v135
	v_and_b32_e32 v135, 0xffff0000, v135
	v_lshlrev_b32_e32 v136, 16, v137
	v_and_b32_e32 v137, 0xffff0000, v137
	v_pk_fma_f32 v[102:103], v[102:103], v[138:139], v[222:223]
	v_pk_fma_f32 v[104:105], v[104:105], v[140:141], v[134:135]
	v_pk_fma_f32 v[98:99], v[98:99], v[142:143], v[224:225]
	v_pk_fma_f32 v[100:101], v[100:101], v[144:145], v[136:137]
	global_store_dwordx4 v[218:219], v[102:105], off offset:512 nt
	global_store_dwordx4 v[218:219], v[98:101], off offset:528 nt
	v_lshl_add_u64 v[218:219], v[218:219], 0, s[12:13]
	global_load_dwordx4 v[130:133], v[220:221], off
	global_load_dwordx4 v[134:137], v[220:221], off offset:256
	s_waitcnt vmcnt(19)
	v_lshlrev_b32_e32 v222, 16, v154
	v_and_b32_e32 v223, 0xffff0000, v154
	v_lshlrev_b32_e32 v224, 16, v156
	v_and_b32_e32 v225, 0xffff0000, v156
	v_lshlrev_b32_e32 v154, 16, v155
	v_and_b32_e32 v155, 0xffff0000, v155
	v_lshlrev_b32_e32 v156, 16, v157
	v_and_b32_e32 v157, 0xffff0000, v157
	v_pk_fma_f32 v[94:95], v[94:95], v[146:147], v[222:223]
	v_pk_fma_f32 v[96:97], v[96:97], v[148:149], v[154:155]
	v_pk_fma_f32 v[90:91], v[90:91], v[150:151], v[224:225]
	v_pk_fma_f32 v[92:93], v[92:93], v[152:153], v[156:157]
	global_store_dwordx4 v[218:219], v[94:97], off nt
	global_store_dwordx4 v[218:219], v[90:93], off offset:16 nt
	s_waitcnt vmcnt(20)
	v_lshlrev_b32_e32 v222, 16, v158
	v_and_b32_e32 v223, 0xffff0000, v158
	v_lshlrev_b32_e32 v224, 16, v160
	v_and_b32_e32 v225, 0xffff0000, v160
	v_lshlrev_b32_e32 v158, 16, v159
	v_and_b32_e32 v159, 0xffff0000, v159
	v_lshlrev_b32_e32 v160, 16, v161
	v_and_b32_e32 v161, 0xffff0000, v161
	v_pk_fma_f32 v[86:87], v[86:87], v[138:139], v[222:223]
	v_pk_fma_f32 v[88:89], v[88:89], v[140:141], v[158:159]
	v_pk_fma_f32 v[82:83], v[82:83], v[142:143], v[224:225]
	v_pk_fma_f32 v[84:85], v[84:85], v[144:145], v[160:161]
	global_store_dwordx4 v[218:219], v[86:89], off offset:512 nt
	global_store_dwordx4 v[218:219], v[82:85], off offset:528 nt
	v_lshl_add_u64 v[218:219], v[218:219], 0, s[10:11]
	s_waitcnt vmcnt(17)
	v_lshlrev_b32_e32 v222, 16, v162
	v_and_b32_e32 v223, 0xffff0000, v162
	v_lshlrev_b32_e32 v224, 16, v164
	v_and_b32_e32 v225, 0xffff0000, v164
	v_lshlrev_b32_e32 v162, 16, v163
	v_and_b32_e32 v163, 0xffff0000, v163
	v_lshlrev_b32_e32 v164, 16, v165
	v_and_b32_e32 v165, 0xffff0000, v165
	v_pk_fma_f32 v[78:79], v[78:79], v[146:147], v[222:223]
	v_pk_fma_f32 v[80:81], v[80:81], v[148:149], v[162:163]
	v_pk_fma_f32 v[74:75], v[74:75], v[150:151], v[224:225]
	v_pk_fma_f32 v[76:77], v[76:77], v[152:153], v[164:165]
	global_store_dwordx4 v[218:219], v[78:81], off nt
	global_store_dwordx4 v[218:219], v[74:77], off offset:16 nt
	s_waitcnt vmcnt(18)
	v_lshlrev_b32_e32 v222, 16, v166
	v_and_b32_e32 v223, 0xffff0000, v166
	v_lshlrev_b32_e32 v224, 16, v168
	v_and_b32_e32 v225, 0xffff0000, v168
	v_lshlrev_b32_e32 v166, 16, v167
	v_and_b32_e32 v167, 0xffff0000, v167
	v_lshlrev_b32_e32 v168, 16, v169
	v_and_b32_e32 v169, 0xffff0000, v169
	v_pk_fma_f32 v[70:71], v[70:71], v[138:139], v[222:223]
	v_pk_fma_f32 v[72:73], v[72:73], v[140:141], v[166:167]
	v_pk_fma_f32 v[66:67], v[66:67], v[142:143], v[224:225]
	v_pk_fma_f32 v[68:69], v[68:69], v[144:145], v[168:169]
	global_store_dwordx4 v[218:219], v[70:73], off offset:512 nt
	global_store_dwordx4 v[218:219], v[66:69], off offset:528 nt
	v_lshl_add_u64 v[218:219], v[218:219], 0, s[10:11]
	s_waitcnt vmcnt(15)
	v_lshlrev_b32_e32 v222, 16, v170
	v_and_b32_e32 v223, 0xffff0000, v170
	v_lshlrev_b32_e32 v224, 16, v172
	v_and_b32_e32 v225, 0xffff0000, v172
	v_lshlrev_b32_e32 v170, 16, v171
	v_and_b32_e32 v171, 0xffff0000, v171
	v_lshlrev_b32_e32 v172, 16, v173
	v_and_b32_e32 v173, 0xffff0000, v173
	v_pk_fma_f32 v[62:63], v[62:63], v[146:147], v[222:223]
	v_pk_fma_f32 v[64:65], v[64:65], v[148:149], v[170:171]
	v_pk_fma_f32 v[58:59], v[58:59], v[150:151], v[224:225]
	v_pk_fma_f32 v[60:61], v[60:61], v[152:153], v[172:173]
	global_store_dwordx4 v[218:219], v[62:65], off nt
	global_store_dwordx4 v[218:219], v[58:61], off offset:16 nt
	s_waitcnt vmcnt(16)
	v_lshlrev_b32_e32 v222, 16, v174
	v_and_b32_e32 v223, 0xffff0000, v174
	v_lshlrev_b32_e32 v224, 16, v176
	v_and_b32_e32 v225, 0xffff0000, v176
	v_lshlrev_b32_e32 v174, 16, v175
	v_and_b32_e32 v175, 0xffff0000, v175
	v_lshlrev_b32_e32 v176, 16, v177
	v_and_b32_e32 v177, 0xffff0000, v177
	v_pk_fma_f32 v[54:55], v[54:55], v[138:139], v[222:223]
	v_pk_fma_f32 v[56:57], v[56:57], v[140:141], v[174:175]
	v_pk_fma_f32 v[50:51], v[50:51], v[142:143], v[224:225]
	v_pk_fma_f32 v[52:53], v[52:53], v[144:145], v[176:177]
	global_store_dwordx4 v[218:219], v[54:57], off offset:512 nt
	global_store_dwordx4 v[218:219], v[50:53], off offset:528 nt
	v_lshl_add_u64 v[218:219], v[218:219], 0, s[10:11]
	s_waitcnt vmcnt(13)
	v_lshlrev_b32_e32 v222, 16, v130
	v_and_b32_e32 v223, 0xffff0000, v130
	v_lshlrev_b32_e32 v224, 16, v132
	v_and_b32_e32 v225, 0xffff0000, v132
	v_lshlrev_b32_e32 v130, 16, v131
	v_and_b32_e32 v131, 0xffff0000, v131
	v_lshlrev_b32_e32 v132, 16, v133
	v_and_b32_e32 v133, 0xffff0000, v133
	v_pk_fma_f32 v[46:47], v[46:47], v[146:147], v[222:223]
	v_pk_fma_f32 v[48:49], v[48:49], v[148:149], v[130:131]
	v_pk_fma_f32 v[42:43], v[42:43], v[150:151], v[224:225]
	v_pk_fma_f32 v[44:45], v[44:45], v[152:153], v[132:133]
	global_store_dwordx4 v[218:219], v[46:49], off nt
	global_store_dwordx4 v[218:219], v[42:45], off offset:16 nt
	s_waitcnt vmcnt(14)
	v_lshlrev_b32_e32 v222, 16, v134
	v_and_b32_e32 v223, 0xffff0000, v134
	v_lshlrev_b32_e32 v224, 16, v136
	v_and_b32_e32 v225, 0xffff0000, v136
	v_lshlrev_b32_e32 v134, 16, v135
	v_and_b32_e32 v135, 0xffff0000, v135
	v_lshlrev_b32_e32 v136, 16, v137
	v_and_b32_e32 v137, 0xffff0000, v137
	v_pk_fma_f32 v[38:39], v[38:39], v[138:139], v[222:223]
	v_pk_fma_f32 v[40:41], v[40:41], v[140:141], v[134:135]
	v_pk_fma_f32 v[34:35], v[34:35], v[142:143], v[224:225]
	v_pk_fma_f32 v[36:37], v[36:37], v[144:145], v[136:137]
	global_store_dwordx4 v[218:219], v[38:41], off offset:512 nt
	global_store_dwordx4 v[218:219], v[34:37], off offset:528 nt
	v_readlane_b32 s72, v253, 57
	v_readlane_b32 s73, v253, 58
	v_readlane_b32 s80, v254, 51
	v_readlane_b32 s81, v254, 52
	v_readlane_b32 s66, v254, 58
	v_readlane_b32 s67, v254, 59
	v_readlane_b32 s54, v253, 59
	v_readlane_b32 s55, v253, 60
	s_branch .LBB0_506
.Lepr_fromin:
	s_and_b64 vcc, exec, s[66:67]
	s_cbranch_vccz .Lepr_general
	s_load_dwordx4 s[64:67], s[0:1], 0x0
	s_lshl_b32 s17, s34, 8
	s_and_b64 s[80:81], s[52:53], exec
	s_waitcnt lgkmcnt(0)
	s_cselect_b32 s55, s65, s67
	s_cselect_b32 s54, s64, s66
	s_add_i32 s70, s17, 0xffffe000
	s_and_b64 s[52:53], s[52:53], exec
	s_cselect_b32 s70, s17, s70
	v_add_u32_e32 v130, s70, v241
	v_ashrrev_i32_e32 v131, 31, v130
	v_lshlrev_b64 v[130:131], 12, v[130:131]
	v_lshl_add_u64 v[130:131], v[220:221], 2, v[130:131]
	v_lshl_add_u64 v[132:133], v[130:131], 0, s[54:55]
	s_load_dwordx4 s[64:67], s[0:1], 0xb8
	s_mov_b64 s[52:53], 0x8000
	s_mov_b64 s[14:15], 0x28000
	v_add_u32_e32 v134, s17, v241
	v_ashrrev_i32_e32 v135, 31, v134
	v_lshlrev_b64 v[134:135], 11, v[134:135]
	v_lshl_add_u64 v[134:135], v[220:221], 1, v[134:135]
	s_waitcnt lgkmcnt(0)
	s_add_u32 s54, s66, 0xe800000
	s_addc_u32 s55, s67, 0
	v_mov_b32_e32 v220, v132
	v_mov_b32_e32 v221, v133
	v_lshl_add_u64 v[216:217], v[134:135], 0, s[54:55]
	s_mov_b64 s[10:11], 0x10000
	s_mov_b64 s[12:13], 0x50000
	s_add_u32 s54, s66, 0x6000000
	s_addc_u32 s55, s67, 0
	v_lshl_add_u64 v[218:219], v[134:135], 0, s[54:55]
	global_load_dwordx4 v[154:157], v[220:221], off nt
	global_load_dwordx4 v[158:161], v[220:221], off offset:16 nt
	global_load_dwordx4 v[162:165], v[220:221], off offset:512 nt
	global_load_dwordx4 v[166:169], v[220:221], off offset:528 nt
	v_lshl_add_u64 v[220:221], v[220:221], 0, s[10:11]
	global_load_dwordx4 v[170:173], v[220:221], off nt
	global_load_dwordx4 v[174:177], v[220:221], off offset:16 nt
	global_load_dwordx4 v[130:133], v[220:221], off offset:512 nt
	global_load_dwordx4 v[134:137], v[220:221], off offset:528 nt
	v_lshl_add_u64 v[220:221], v[220:221], 0, s[10:11]
	v_pk_mul_f32 v[146:147], v[146:147], v[192:193]
	v_pk_mul_f32 v[148:149], v[148:149], v[192:193]
	v_pk_mul_f32 v[150:151], v[150:151], v[192:193]
	v_pk_mul_f32 v[152:153], v[152:153], v[192:193]
	v_pk_mul_f32 v[138:139], v[138:139], v[192:193]
	v_pk_mul_f32 v[140:141], v[140:141], v[192:193]
	v_pk_mul_f32 v[142:143], v[142:143], v[192:193]
	v_pk_mul_f32 v[144:145], v[144:145], v[192:193]
	s_waitcnt vmcnt(6)
	v_pk_fma_f32 v[30:31], v[30:31], v[146:147], v[154:155]
	v_pk_fma_f32 v[32:33], v[32:33], v[148:149], v[156:157]
	v_pk_fma_f32 v[26:27], v[26:27], v[150:151], v[158:159]
	v_pk_fma_f32 v[28:29], v[28:29], v[152:153], v[160:161]
	v_cvt_pk_bf16_f32 v222, v30, v31
	v_cvt_pk_bf16_f32 v223, v32, v33
	v_cvt_pk_bf16_f32 v224, v26, v27
	v_cvt_pk_bf16_f32 v225, v28, v29
	global_store_dwordx4 v[216:217], v[222:225], off
	v_pk_mul_f32 v[226:227], v[30:31], v[30:31]
	v_pk_fma_f32 v[226:227], v[32:33], v[32:33], v[226:227]
	v_pk_fma_f32 v[226:227], v[26:27], v[26:27], v[226:227]
	v_pk_fma_f32 v[226:227], v[28:29], v[28:29], v[226:227]
	v_pk_mul_f32 v[30:31], v[30:31], v[208:209]
	v_pk_mul_f32 v[32:33], v[32:33], v[210:211]
	v_pk_mul_f32 v[26:27], v[26:27], v[212:213]
	v_pk_mul_f32 v[28:29], v[28:29], v[214:215]
	v_cvt_pk_bf16_f32 v154, v30, v31
	v_cvt_pk_bf16_f32 v155, v32, v33
	v_cvt_pk_bf16_f32 v156, v26, v27
	v_cvt_pk_bf16_f32 v157, v28, v29
	global_store_dwordx4 v[218:219], v[154:157], off
	s_waitcnt vmcnt(6)
	v_pk_fma_f32 v[22:23], v[22:23], v[138:139], v[162:163]
	v_pk_fma_f32 v[24:25], v[24:25], v[140:141], v[164:165]
	v_pk_fma_f32 v[14:15], v[14:15], v[142:143], v[166:167]
	v_pk_fma_f32 v[16:17], v[16:17], v[144:145], v[168:169]
	v_cvt_pk_bf16_f32 v222, v22, v23
	v_cvt_pk_bf16_f32 v223, v24, v25
	v_cvt_pk_bf16_f32 v224, v14, v15
	v_cvt_pk_bf16_f32 v225, v16, v17
	global_store_dwordx4 v[216:217], v[222:225], off offset:256
	v_pk_fma_f32 v[226:227], v[22:23], v[22:23], v[226:227]
	v_pk_fma_f32 v[226:227], v[24:25], v[24:25], v[226:227]
	v_pk_fma_f32 v[226:227], v[14:15], v[14:15], v[226:227]
	v_pk_fma_f32 v[226:227], v[16:17], v[16:17], v[226:227]
	v_pk_mul_f32 v[22:23], v[22:23], v[200:201]
	v_pk_mul_f32 v[24:25], v[24:25], v[202:203]
	v_pk_mul_f32 v[14:15], v[14:15], v[204:205]
	v_pk_mul_f32 v[16:17], v[16:17], v[206:207]
	v_cvt_pk_bf16_f32 v162, v22, v23
	v_cvt_pk_bf16_f32 v163, v24, v25
	v_cvt_pk_bf16_f32 v164, v14, v15
	v_cvt_pk_bf16_f32 v165, v16, v17
	global_store_dwordx4 v[218:219], v[162:165], off offset:256
	v_add_f32_e32 v228, v226, v227
	v_lshl_add_u64 v[216:217], v[216:217], 0, s[52:53]
	v_lshl_add_u64 v[218:219], v[218:219], 0, s[52:53]
	global_load_dwordx4 v[154:157], v[220:221], off nt
	global_load_dwordx4 v[158:161], v[220:221], off offset:16 nt
	global_load_dwordx4 v[162:165], v[220:221], off offset:512 nt
	global_load_dwordx4 v[166:169], v[220:221], off offset:528 nt
	v_lshl_add_u64 v[220:221], v[220:221], 0, s[10:11]
	s_waitcnt vmcnt(10)
	v_pk_fma_f32 v[18:19], v[18:19], v[146:147], v[170:171]
	v_pk_fma_f32 v[20:21], v[20:21], v[148:149], v[172:173]
	v_pk_fma_f32 v[10:11], v[10:11], v[150:151], v[174:175]
	v_pk_fma_f32 v[12:13], v[12:13], v[152:153], v[176:177]
	v_cvt_pk_bf16_f32 v222, v18, v19
	v_cvt_pk_bf16_f32 v223, v20, v21
	v_cvt_pk_bf16_f32 v224, v10, v11
	v_cvt_pk_bf16_f32 v225, v12, v13
	global_store_dwordx4 v[216:217], v[222:225], off
	v_pk_mul_f32 v[226:227], v[18:19], v[18:19]
	v_pk_fma_f32 v[226:227], v[20:21], v[20:21], v[226:227]
	v_pk_fma_f32 v[226:227], v[10:11], v[10:11], v[226:227]
	v_pk_fma_f32 v[226:227], v[12:13], v[12:13], v[226:227]
	v_pk_mul_f32 v[18:19], v[18:19], v[208:209]
	v_pk_mul_f32 v[20:21], v[20:21], v[210:211]
	v_pk_mul_f32 v[10:11], v[10:11], v[212:213]
	v_pk_mul_f32 v[12:13], v[12:13], v[214:215]
	v_cvt_pk_bf16_f32 v170, v18, v19
	v_cvt_pk_bf16_f32 v171, v20, v21
	v_cvt_pk_bf16_f32 v172, v10, v11
	v_cvt_pk_bf16_f32 v173, v12, v13
	global_store_dwordx4 v[218:219], v[170:173], off
	s_waitcnt vmcnt(10)
	v_pk_fma_f32 v[6:7], v[6:7], v[138:139], v[130:131]
	v_pk_fma_f32 v[8:9], v[8:9], v[140:141], v[132:133]
	v_pk_fma_f32 v[2:3], v[2:3], v[142:143], v[134:135]
	v_pk_fma_f32 v[4:5], v[4:5], v[144:145], v[136:137]
	v_cvt_pk_bf16_f32 v222, v6, v7
	v_cvt_pk_bf16_f32 v223, v8, v9
	v_cvt_pk_bf16_f32 v224, v2, v3
	v_cvt_pk_bf16_f32 v225, v4, v5
	global_store_dwordx4 v[216:217], v[222:225], off offset:256
	v_pk_fma_f32 v[226:227], v[6:7], v[6:7], v[226:227]
	v_pk_fma_f32 v[226:227], v[8:9], v[8:9], v[226:227]
	v_pk_fma_f32 v[226:227], v[2:3], v[2:3], v[226:227]
	v_pk_fma_f32 v[226:227], v[4:5], v[4:5], v[226:227]
	v_pk_mul_f32 v[6:7], v[6:7], v[200:201]
	v_pk_mul_f32 v[8:9], v[8:9], v[202:203]
	v_pk_mul_f32 v[2:3], v[2:3], v[204:205]
	v_pk_mul_f32 v[4:5], v[4:5], v[206:207]
	v_cvt_pk_bf16_f32 v130, v6, v7
	v_cvt_pk_bf16_f32 v131, v8, v9
	v_cvt_pk_bf16_f32 v132, v2, v3
	v_cvt_pk_bf16_f32 v133, v4, v5
	global_store_dwordx4 v[218:219], v[130:133], off offset:256
	v_add_f32_e32 v229, v226, v227
	v_lshl_add_u64 v[216:217], v[216:217], 0, s[52:53]
	v_lshl_add_u64 v[218:219], v[218:219], 0, s[52:53]
	global_load_dwordx4 v[170:173], v[220:221], off nt
	global_load_dwordx4 v[174:177], v[220:221], off offset:16 nt
	global_load_dwordx4 v[130:133], v[220:221], off offset:512 nt
	global_load_dwordx4 v[134:137], v[220:221], off offset:528 nt
	v_lshl_add_u64 v[220:221], v[220:221], 0, s[12:13]
	s_waitcnt vmcnt(10)
	v_pk_fma_f32 v[126:127], v[126:127], v[146:147], v[154:155]
	v_pk_fma_f32 v[128:129], v[128:129], v[148:149], v[156:157]
	v_pk_fma_f32 v[122:123], v[122:123], v[150:151], v[158:159]
	v_pk_fma_f32 v[124:125], v[124:125], v[152:153], v[160:161]
	v_cvt_pk_bf16_f32 v222, v126, v127
	v_cvt_pk_bf16_f32 v223, v128, v129
	v_cvt_pk_bf16_f32 v224, v122, v123
	v_cvt_pk_bf16_f32 v225, v124, v125
	global_store_dwordx4 v[216:217], v[222:225], off
	v_pk_mul_f32 v[226:227], v[126:127], v[126:127]
	v_pk_fma_f32 v[226:227], v[128:129], v[128:129], v[226:227]
	v_pk_fma_f32 v[226:227], v[122:123], v[122:123], v[226:227]
	v_pk_fma_f32 v[226:227], v[124:125], v[124:125], v[226:227]
	v_pk_mul_f32 v[126:127], v[126:127], v[208:209]
	v_pk_mul_f32 v[128:129], v[128:129], v[210:211]
	v_pk_mul_f32 v[122:123], v[122:123], v[212:213]
	v_pk_mul_f32 v[124:125], v[124:125], v[214:215]
	v_cvt_pk_bf16_f32 v154, v126, v127
	v_cvt_pk_bf16_f32 v155, v128, v129
	v_cvt_pk_bf16_f32 v156, v122, v123
	v_cvt_pk_bf16_f32 v157, v124, v125
	global_store_dwordx4 v[218:219], v[154:157], off
	s_waitcnt vmcnt(10)
	v_pk_fma_f32 v[118:119], v[118:119], v[138:139], v[162:163]
	v_pk_fma_f32 v[120:121], v[120:121], v[140:141], v[164:165]
	v_pk_fma_f32 v[114:115], v[114:115], v[142:143], v[166:167]
	v_pk_fma_f32 v[116:117], v[116:117], v[144:145], v[168:169]
	v_cvt_pk_bf16_f32 v222, v118, v119
	v_cvt_pk_bf16_f32 v223, v120, v121
	v_cvt_pk_bf16_f32 v224, v114, v115
	v_cvt_pk_bf16_f32 v225, v116, v117
	global_store_dwordx4 v[216:217], v[222:225], off offset:256
	v_pk_fma_f32 v[226:227], v[118:119], v[118:119], v[226:227]
	v_pk_fma_f32 v[226:227], v[120:121], v[120:121], v[226:227]
	v_pk_fma_f32 v[226:227], v[114:115], v[114:115], v[226:227]
	v_pk_fma_f32 v[226:227], v[116:117], v[116:117], v[226:227]
	v_pk_mul_f32 v[118:119], v[118:119], v[200:201]
	v_pk_mul_f32 v[120:121], v[120:121], v[202:203]
	v_pk_mul_f32 v[114:115], v[114:115], v[204:205]
	v_pk_mul_f32 v[116:117], v[116:117], v[206:207]
	v_cvt_pk_bf16_f32 v162, v118, v119
	v_cvt_pk_bf16_f32 v163, v120, v121
	v_cvt_pk_bf16_f32 v164, v114, v115
	v_cvt_pk_bf16_f32 v165, v116, v117
	global_store_dwordx4 v[218:219], v[162:165], off offset:256
	v_add_f32_e32 v22, v226, v227
	v_lshl_add_u64 v[216:217], v[216:217], 0, s[52:53]
	v_lshl_add_u64 v[218:219], v[218:219], 0, s[52:53]
	global_load_dwordx4 v[154:157], v[220:221], off nt
	global_load_dwordx4 v[158:161], v[220:221], off offset:16 nt
	global_load_dwordx4 v[162:165], v[220:221], off offset:512 nt
	global_load_dwordx4 v[166:169], v[220:221], off offset:528 nt
	v_lshl_add_u64 v[220:221], v[220:221], 0, s[10:11]
	s_waitcnt vmcnt(10)
	v_pk_fma_f32 v[110:111], v[110:111], v[146:147], v[170:171]
	v_pk_fma_f32 v[112:113], v[112:113], v[148:149], v[172:173]
	v_pk_fma_f32 v[106:107], v[106:107], v[150:151], v[174:175]
	v_pk_fma_f32 v[108:109], v[108:109], v[152:153], v[176:177]
	v_cvt_pk_bf16_f32 v222, v110, v111
	v_cvt_pk_bf16_f32 v223, v112, v113
	v_cvt_pk_bf16_f32 v224, v106, v107
	v_cvt_pk_bf16_f32 v225, v108, v109
	global_store_dwordx4 v[216:217], v[222:225], off
	v_pk_mul_f32 v[226:227], v[110:111], v[110:111]
	v_pk_fma_f32 v[226:227], v[112:113], v[112:113], v[226:227]
	v_pk_fma_f32 v[226:227], v[106:107], v[106:107], v[226:227]
	v_pk_fma_f32 v[226:227], v[108:109], v[108:109], v[226:227]
	v_pk_mul_f32 v[110:111], v[110:111], v[208:209]
	v_pk_mul_f32 v[112:113], v[112:113], v[210:211]
	v_pk_mul_f32 v[106:107], v[106:107], v[212:213]
	v_pk_mul_f32 v[108:109], v[108:109], v[214:215]
	v_cvt_pk_bf16_f32 v170, v110, v111
	v_cvt_pk_bf16_f32 v171, v112, v113
	v_cvt_pk_bf16_f32 v172, v106, v107
	v_cvt_pk_bf16_f32 v173, v108, v109
	global_store_dwordx4 v[218:219], v[170:173], off
	s_waitcnt vmcnt(10)
	v_pk_fma_f32 v[102:103], v[102:103], v[138:139], v[130:131]
	v_pk_fma_f32 v[104:105], v[104:105], v[140:141], v[132:133]
	v_pk_fma_f32 v[98:99], v[98:99], v[142:143], v[134:135]
	v_pk_fma_f32 v[100:101], v[100:101], v[144:145], v[136:137]
	v_cvt_pk_bf16_f32 v222, v102, v103
	v_cvt_pk_bf16_f32 v223, v104, v105
	v_cvt_pk_bf16_f32 v224, v98, v99
	v_cvt_pk_bf16_f32 v225, v100, v101
	global_store_dwordx4 v[216:217], v[222:225], off offset:256
	v_pk_fma_f32 v[226:227], v[102:103], v[102:103], v[226:227]
	v_pk_fma_f32 v[226:227], v[104:105], v[104:105], v[226:227]
	v_pk_fma_f32 v[226:227], v[98:99], v[98:99], v[226:227]
	v_pk_fma_f32 v[226:227], v[100:101], v[100:101], v[226:227]
	v_pk_mul_f32 v[102:103], v[102:103], v[200:201]
	v_pk_mul_f32 v[104:105], v[104:105], v[202:203]
	v_pk_mul_f32 v[98:99], v[98:99], v[204:205]
	v_pk_mul_f32 v[100:101], v[100:101], v[206:207]
	v_cvt_pk_bf16_f32 v130, v102, v103
	v_cvt_pk_bf16_f32 v131, v104, v105
	v_cvt_pk_bf16_f32 v132, v98, v99
	v_cvt_pk_bf16_f32 v133, v100, v101
	global_store_dwordx4 v[218:219], v[130:133], off offset:256
	v_add_f32_e32 v23, v226, v227
	v_lshl_add_u64 v[216:217], v[216:217], 0, s[14:15]
	v_lshl_add_u64 v[218:219], v[218:219], 0, s[14:15]
	global_load_dwordx4 v[170:173], v[220:221], off nt
	global_load_dwordx4 v[174:177], v[220:221], off offset:16 nt
	global_load_dwordx4 v[130:133], v[220:221], off offset:512 nt
	global_load_dwordx4 v[134:137], v[220:221], off offset:528 nt
	v_lshl_add_u64 v[220:221], v[220:221], 0, s[10:11]
	s_waitcnt vmcnt(10)
	v_pk_fma_f32 v[94:95], v[94:95], v[146:147], v[154:155]
	v_pk_fma_f32 v[96:97], v[96:97], v[148:149], v[156:157]
	v_pk_fma_f32 v[90:91], v[90:91], v[150:151], v[158:159]
	v_pk_fma_f32 v[92:93], v[92:93], v[152:153], v[160:161]
	v_cvt_pk_bf16_f32 v222, v94, v95
	v_cvt_pk_bf16_f32 v223, v96, v97
	v_cvt_pk_bf16_f32 v224, v90, v91
	v_cvt_pk_bf16_f32 v225, v92, v93
	global_store_dwordx4 v[216:217], v[222:225], off
	v_pk_mul_f32 v[226:227], v[94:95], v[94:95]
	v_pk_fma_f32 v[226:227], v[96:97], v[96:97], v[226:227]
	v_pk_fma_f32 v[226:227], v[90:91], v[90:91], v[226:227]
	v_pk_fma_f32 v[226:227], v[92:93], v[92:93], v[226:227]
	v_pk_mul_f32 v[94:95], v[94:95], v[208:209]
	v_pk_mul_f32 v[96:97], v[96:97], v[210:211]
	v_pk_mul_f32 v[90:91], v[90:91], v[212:213]
	v_pk_mul_f32 v[92:93], v[92:93], v[214:215]
	v_cvt_pk_bf16_f32 v154, v94, v95
	v_cvt_pk_bf16_f32 v155, v96, v97
	v_cvt_pk_bf16_f32 v156, v90, v91
	v_cvt_pk_bf16_f32 v157, v92, v93
	global_store_dwordx4 v[218:219], v[154:157], off
	s_waitcnt vmcnt(10)
	v_pk_fma_f32 v[86:87], v[86:87], v[138:139], v[162:163]
	v_pk_fma_f32 v[88:89], v[88:89], v[140:141], v[164:165]
	v_pk_fma_f32 v[82:83], v[82:83], v[142:143], v[166:167]
	v_pk_fma_f32 v[84:85], v[84:85], v[144:145], v[168:169]
	v_cvt_pk_bf16_f32 v222, v86, v87
	v_cvt_pk_bf16_f32 v223, v88, v89
	v_cvt_pk_bf16_f32 v224, v82, v83
	v_cvt_pk_bf16_f32 v225, v84, v85
	global_store_dwordx4 v[216:217], v[222:225], off offset:256
	v_pk_fma_f32 v[226:227], v[86:87], v[86:87], v[226:227]
	v_pk_fma_f32 v[226:227], v[88:89], v[88:89], v[226:227]
	v_pk_fma_f32 v[226:227], v[82:83], v[82:83], v[226:227]
	v_pk_fma_f32 v[226:227], v[84:85], v[84:85], v[226:227]
	v_pk_mul_f32 v[86:87], v[86:87], v[200:201]
	v_pk_mul_f32 v[88:89], v[88:89], v[202:203]
	v_pk_mul_f32 v[82:83], v[82:83], v[204:205]
	v_pk_mul_f32 v[84:85], v[84:85], v[206:207]
	v_cvt_pk_bf16_f32 v162, v86, v87
	v_cvt_pk_bf16_f32 v163, v88, v89
	v_cvt_pk_bf16_f32 v164, v82, v83
	v_cvt_pk_bf16_f32 v165, v84, v85
	global_store_dwordx4 v[218:219], v[162:165], off offset:256
	v_add_f32_e32 v24, v226, v227
	v_lshl_add_u64 v[216:217], v[216:217], 0, s[52:53]
	v_lshl_add_u64 v[218:219], v[218:219], 0, s[52:53]
	global_load_dwordx4 v[154:157], v[220:221], off nt
	global_load_dwordx4 v[158:161], v[220:221], off offset:16 nt
	global_load_dwordx4 v[162:165], v[220:221], off offset:512 nt
	global_load_dwordx4 v[166:169], v[220:221], off offset:528 nt
	v_lshl_add_u64 v[220:221], v[220:221], 0, s[10:11]
	s_waitcnt vmcnt(10)
	v_pk_fma_f32 v[78:79], v[78:79], v[146:147], v[170:171]
	v_pk_fma_f32 v[80:81], v[80:81], v[148:149], v[172:173]
	v_pk_fma_f32 v[74:75], v[74:75], v[150:151], v[174:175]
	v_pk_fma_f32 v[76:77], v[76:77], v[152:153], v[176:177]
	v_cvt_pk_bf16_f32 v222, v78, v79
	v_cvt_pk_bf16_f32 v223, v80, v81
	v_cvt_pk_bf16_f32 v224, v74, v75
	v_cvt_pk_bf16_f32 v225, v76, v77
	global_store_dwordx4 v[216:217], v[222:225], off
	v_pk_mul_f32 v[226:227], v[78:79], v[78:79]
	v_pk_fma_f32 v[226:227], v[80:81], v[80:81], v[226:227]
	v_pk_fma_f32 v[226:227], v[74:75], v[74:75], v[226:227]
	v_pk_fma_f32 v[226:227], v[76:77], v[76:77], v[226:227]
	v_pk_mul_f32 v[78:79], v[78:79], v[208:209]
	v_pk_mul_f32 v[80:81], v[80:81], v[210:211]
	v_pk_mul_f32 v[74:75], v[74:75], v[212:213]
	v_pk_mul_f32 v[76:77], v[76:77], v[214:215]
	v_cvt_pk_bf16_f32 v170, v78, v79
	v_cvt_pk_bf16_f32 v171, v80, v81
	v_cvt_pk_bf16_f32 v172, v74, v75
	v_cvt_pk_bf16_f32 v173, v76, v77
	global_store_dwordx4 v[218:219], v[170:173], off
	s_waitcnt vmcnt(10)
	v_pk_fma_f32 v[70:71], v[70:71], v[138:139], v[130:131]
	v_pk_fma_f32 v[72:73], v[72:73], v[140:141], v[132:133]
	v_pk_fma_f32 v[66:67], v[66:67], v[142:143], v[134:135]
	v_pk_fma_f32 v[68:69], v[68:69], v[144:145], v[136:137]
	v_cvt_pk_bf16_f32 v222, v70, v71
	v_cvt_pk_bf16_f32 v223, v72, v73
	v_cvt_pk_bf16_f32 v224, v66, v67
	v_cvt_pk_bf16_f32 v225, v68, v69
	global_store_dwordx4 v[216:217], v[222:225], off offset:256
	v_pk_fma_f32 v[226:227], v[70:71], v[70:71], v[226:227]
	v_pk_fma_f32 v[226:227], v[72:73], v[72:73], v[226:227]
	v_pk_fma_f32 v[226:227], v[66:67], v[66:67], v[226:227]
	v_pk_fma_f32 v[226:227], v[68:69], v[68:69], v[226:227]
	v_pk_mul_f32 v[70:71], v[70:71], v[200:201]
	v_pk_mul_f32 v[72:73], v[72:73], v[202:203]
	v_pk_mul_f32 v[66:67], v[66:67], v[204:205]
	v_pk_mul_f32 v[68:69], v[68:69], v[206:207]
	v_cvt_pk_bf16_f32 v130, v70, v71
	v_cvt_pk_bf16_f32 v131, v72, v73
	v_cvt_pk_bf16_f32 v132, v66, v67
	v_cvt_pk_bf16_f32 v133, v68, v69
	global_store_dwordx4 v[218:219], v[130:133], off offset:256
	v_add_f32_e32 v25, v226, v227
	v_lshl_add_u64 v[216:217], v[216:217], 0, s[52:53]
	v_lshl_add_u64 v[218:219], v[218:219], 0, s[52:53]
	global_load_dwordx4 v[170:173], v[220:221], off nt
	global_load_dwordx4 v[174:177], v[220:221], off offset:16 nt
	global_load_dwordx4 v[130:133], v[220:221], off offset:512 nt
	global_load_dwordx4 v[134:137], v[220:221], off offset:528 nt
	s_waitcnt vmcnt(10)
	v_pk_fma_f32 v[62:63], v[62:63], v[146:147], v[154:155]
	v_pk_fma_f32 v[64:65], v[64:65], v[148:149], v[156:157]
	v_pk_fma_f32 v[58:59], v[58:59], v[150:151], v[158:159]
	v_pk_fma_f32 v[60:61], v[60:61], v[152:153], v[160:161]
	v_cvt_pk_bf16_f32 v222, v62, v63
	v_cvt_pk_bf16_f32 v223, v64, v65
	v_cvt_pk_bf16_f32 v224, v58, v59
	v_cvt_pk_bf16_f32 v225, v60, v61
	global_store_dwordx4 v[216:217], v[222:225], off
	v_pk_mul_f32 v[226:227], v[62:63], v[62:63]
	v_pk_fma_f32 v[226:227], v[64:65], v[64:65], v[226:227]
	v_pk_fma_f32 v[226:227], v[58:59], v[58:59], v[226:227]
	v_pk_fma_f32 v[226:227], v[60:61], v[60:61], v[226:227]
	v_pk_mul_f32 v[62:63], v[62:63], v[208:209]
	v_pk_mul_f32 v[64:65], v[64:65], v[210:211]
	v_pk_mul_f32 v[58:59], v[58:59], v[212:213]
	v_pk_mul_f32 v[60:61], v[60:61], v[214:215]
	v_cvt_pk_bf16_f32 v154, v62, v63
	v_cvt_pk_bf16_f32 v155, v64, v65
	v_cvt_pk_bf16_f32 v156, v58, v59
	v_cvt_pk_bf16_f32 v157, v60, v61
	global_store_dwordx4 v[218:219], v[154:157], off
	s_waitcnt vmcnt(10)
	v_pk_fma_f32 v[54:55], v[54:55], v[138:139], v[162:163]
	v_pk_fma_f32 v[56:57], v[56:57], v[140:141], v[164:165]
	v_pk_fma_f32 v[50:51], v[50:51], v[142:143], v[166:167]
	v_pk_fma_f32 v[52:53], v[52:53], v[144:145], v[168:169]
	v_cvt_pk_bf16_f32 v222, v54, v55
	v_cvt_pk_bf16_f32 v223, v56, v57
	v_cvt_pk_bf16_f32 v224, v50, v51
	v_cvt_pk_bf16_f32 v225, v52, v53
	global_store_dwordx4 v[216:217], v[222:225], off offset:256
	v_pk_fma_f32 v[226:227], v[54:55], v[54:55], v[226:227]
	v_pk_fma_f32 v[226:227], v[56:57], v[56:57], v[226:227]
	v_pk_fma_f32 v[226:227], v[50:51], v[50:51], v[226:227]
	v_pk_fma_f32 v[226:227], v[52:53], v[52:53], v[226:227]
	v_pk_mul_f32 v[54:55], v[54:55], v[200:201]
	v_pk_mul_f32 v[56:57], v[56:57], v[202:203]
	v_pk_mul_f32 v[50:51], v[50:51], v[204:205]
	v_pk_mul_f32 v[52:53], v[52:53], v[206:207]
	v_cvt_pk_bf16_f32 v162, v54, v55
	v_cvt_pk_bf16_f32 v163, v56, v57
	v_cvt_pk_bf16_f32 v164, v50, v51
	v_cvt_pk_bf16_f32 v165, v52, v53
	global_store_dwordx4 v[218:219], v[162:165], off offset:256
	v_add_f32_e32 v26, v226, v227
	v_lshl_add_u64 v[216:217], v[216:217], 0, s[52:53]
	v_lshl_add_u64 v[218:219], v[218:219], 0, s[52:53]
	s_waitcnt vmcnt(6)
	v_pk_fma_f32 v[46:47], v[46:47], v[146:147], v[170:171]
	v_pk_fma_f32 v[48:49], v[48:49], v[148:149], v[172:173]
	v_pk_fma_f32 v[42:43], v[42:43], v[150:151], v[174:175]
	v_pk_fma_f32 v[44:45], v[44:45], v[152:153], v[176:177]
	v_cvt_pk_bf16_f32 v222, v46, v47
	v_cvt_pk_bf16_f32 v223, v48, v49
	v_cvt_pk_bf16_f32 v224, v42, v43
	v_cvt_pk_bf16_f32 v225, v44, v45
	global_store_dwordx4 v[216:217], v[222:225], off
	v_pk_mul_f32 v[226:227], v[46:47], v[46:47]
	v_pk_fma_f32 v[226:227], v[48:49], v[48:49], v[226:227]
	v_pk_fma_f32 v[226:227], v[42:43], v[42:43], v[226:227]
	v_pk_fma_f32 v[226:227], v[44:45], v[44:45], v[226:227]
	v_pk_mul_f32 v[46:47], v[46:47], v[208:209]
	v_pk_mul_f32 v[48:49], v[48:49], v[210:211]
	v_pk_mul_f32 v[42:43], v[42:43], v[212:213]
	v_pk_mul_f32 v[44:45], v[44:45], v[214:215]
	v_cvt_pk_bf16_f32 v170, v46, v47
	v_cvt_pk_bf16_f32 v171, v48, v49
	v_cvt_pk_bf16_f32 v172, v42, v43
	v_cvt_pk_bf16_f32 v173, v44, v45
	global_store_dwordx4 v[218:219], v[170:173], off
	s_waitcnt vmcnt(6)
	v_pk_fma_f32 v[38:39], v[38:39], v[138:139], v[130:131]
	v_pk_fma_f32 v[40:41], v[40:41], v[140:141], v[132:133]
	v_pk_fma_f32 v[34:35], v[34:35], v[142:143], v[134:135]
	v_pk_fma_f32 v[36:37], v[36:37], v[144:145], v[136:137]
	v_cvt_pk_bf16_f32 v222, v38, v39
	v_cvt_pk_bf16_f32 v223, v40, v41
	v_cvt_pk_bf16_f32 v224, v34, v35
	v_cvt_pk_bf16_f32 v225, v36, v37
	global_store_dwordx4 v[216:217], v[222:225], off offset:256
	v_pk_fma_f32 v[226:227], v[38:39], v[38:39], v[226:227]
	v_pk_fma_f32 v[226:227], v[40:41], v[40:41], v[226:227]
	v_pk_fma_f32 v[226:227], v[34:35], v[34:35], v[226:227]
	v_pk_fma_f32 v[226:227], v[36:37], v[36:37], v[226:227]
	v_pk_mul_f32 v[38:39], v[38:39], v[200:201]
	v_pk_mul_f32 v[40:41], v[40:41], v[202:203]
	v_pk_mul_f32 v[34:35], v[34:35], v[204:205]
	v_pk_mul_f32 v[36:37], v[36:37], v[206:207]
	v_cvt_pk_bf16_f32 v130, v38, v39
	v_cvt_pk_bf16_f32 v131, v40, v41
	v_cvt_pk_bf16_f32 v132, v34, v35
	v_cvt_pk_bf16_f32 v133, v36, v37
	global_store_dwordx4 v[218:219], v[130:133], off offset:256
	v_add_f32_e32 v27, v226, v227
	ds_bpermute_b32 v28, v244, v228
	ds_bpermute_b32 v29, v244, v229
	ds_bpermute_b32 v30, v244, v22
	ds_bpermute_b32 v31, v244, v23
	ds_bpermute_b32 v32, v244, v24
	ds_bpermute_b32 v33, v244, v25
	ds_bpermute_b32 v14, v244, v26
	ds_bpermute_b32 v15, v244, v27
	v_readlane_b32 s12, v254, 44
	s_waitcnt lgkmcnt(0)
	v_add_f32_e32 v228, v228, v28
	v_add_f32_e32 v229, v229, v29
	v_add_f32_e32 v22, v22, v30
	v_add_f32_e32 v23, v23, v31
	v_add_f32_e32 v24, v24, v32
	v_add_f32_e32 v25, v25, v33
	v_add_f32_e32 v26, v26, v14
	v_add_f32_e32 v27, v27, v15
	ds_bpermute_b32 v28, v245, v228
	ds_bpermute_b32 v29, v245, v229
	ds_bpermute_b32 v30, v245, v22
	ds_bpermute_b32 v31, v245, v23
	ds_bpermute_b32 v32, v245, v24
	ds_bpermute_b32 v33, v245, v25
	ds_bpermute_b32 v14, v245, v26
	ds_bpermute_b32 v15, v245, v27
	v_lshl_add_u32 v0, v241, 4, s12
	s_waitcnt lgkmcnt(0)
	v_add_f32_e32 v228, v228, v28
	v_add_f32_e32 v229, v229, v29
	v_add_f32_e32 v22, v22, v30
	v_add_f32_e32 v23, v23, v31
	v_add_f32_e32 v24, v24, v32
	v_add_f32_e32 v25, v25, v33
	v_add_f32_e32 v26, v26, v14
	v_add_f32_e32 v27, v27, v15
	s_and_saveexec_b64 s[10:11], s[88:89]
	ds_write_b32 v0, v228
	ds_write_b32 v0, v229 offset:256
	ds_write_b32 v0, v22 offset:512
	ds_write_b32 v0, v23 offset:768
	ds_write_b32 v0, v24 offset:2048
	ds_write_b32 v0, v25 offset:2304
	ds_write_b32 v0, v26 offset:2560
	ds_write_b32 v0, v27 offset:2816
	v_readlane_b32 s72, v253, 57
	v_readlane_b32 s73, v253, 58
	v_readlane_b32 s80, v254, 51
	v_readlane_b32 s81, v254, 52
	v_readlane_b32 s66, v254, 58
	v_readlane_b32 s67, v254, 59
	v_readlane_b32 s54, v253, 59
	v_readlane_b32 s55, v253, 60
	s_branch .LBB0_503
